# phase 2 as a per-workgroup schedule: attention rounds and conv tile rounds alternate (A: N1 C1 N1 C1 N2, B: N2 C1 N1 C1 N1), the halves of every XCD's workgroups on shifted schedules
# speedup vs baseline: 1.0193x; 1.0000x over previous
.LBB0_1072:
	s_cmp_gt_i32 s66, 1
	s_mov_b64 s[0:1], -1
	s_cbranch_scc0 .LBB0_1115
	s_mov_b32 s98, 0
.Lp2_disp:
	s_lshr_b32 vcc_lo, s98, 24
	s_cmp_eq_u32 vcc_lo, 5
	s_cbranch_scc1 .Lp2_done
	s_and_b32 s98, s98, 0xff000000
	s_mov_b32 vcc_hi, 0
	s_bitcmp1_b32 vcc_lo, 0
	s_cbranch_scc1 .Lp2_cvsel
	s_bitcmp1_b32 s99, 3
	s_cbranch_scc0 .Lp2_grpB
	s_cmp_eq_u32 vcc_lo, 0
	s_cselect_b32 vcc_hi, 0x100, vcc_hi
	s_cmp_eq_u32 vcc_lo, 2
	s_cselect_b32 vcc_hi, 0x201, vcc_hi
	s_cmp_eq_u32 vcc_lo, 4
	s_cselect_b32 vcc_hi, 0x402, vcc_hi
	s_or_b32 s98, s98, vcc_hi
	s_branch .Lp2_na
.Lp2_grpB:
	s_cmp_eq_u32 vcc_lo, 0
	s_cselect_b32 vcc_hi, 0x200, vcc_hi
	s_cmp_eq_u32 vcc_lo, 2
	s_cselect_b32 vcc_hi, 0x302, vcc_hi
	s_cmp_eq_u32 vcc_lo, 4
	s_cselect_b32 vcc_hi, 0x403, vcc_hi
	s_or_b32 s98, s98, vcc_hi
	s_branch .Lp2_na
.Lp2_cvsel:
	s_mov_b32 vcc_hi, 0x201
	s_cmp_eq_u32 vcc_lo, 1
	s_cselect_b32 vcc_hi, 0x100, vcc_hi
	s_or_b32 s98, s98, vcc_hi
	s_branch .LBB0_1074

.Lna_nopf:
	v_max3_f32 v233, v8, v9, v10
	v_max_f32_e32 v233, v233, v11
	v_max_f32_e32 v233, v233, v12
	v_max_f32_e32 v233, v233, v13
	v_max_f32_e32 v233, v233, v14
	v_max_f32_e32 v233, v233, v15
	v_max_f32_e32 v233, v233, v16
	v_max_f32_e32 v233, v233, v17
	v_max_f32_e32 v233, v233, v18
	v_max_f32_e32 v233, v233, v19
	v_max_f32_e32 v233, v233, v20
	v_max_f32_e32 v233, v233, v21
	v_max_f32_e32 v233, v233, v22
	v_max_f32_e32 v233, v233, v23
	v_max_f32_e32 v233, v233, v24
	v_max_f32_e32 v233, v233, v25
	v_max_f32_e32 v233, v233, v26
	v_max_f32_e32 v233, v233, v27
	v_max_f32_e32 v233, v233, v28
	v_max_f32_e32 v233, v233, v29
	v_max_f32_e32 v233, v233, v30
	v_max_f32_e32 v233, v233, v31
	v_max_f32_e32 v233, v233, v32
	v_max_f32_e32 v233, v233, v33
	v_max_f32_e32 v233, v233, v34
	v_max_f32_e32 v233, v233, v35
	v_max_f32_e32 v233, v233, v36
	v_max_f32_e32 v233, v233, v37
	v_max_f32_e32 v233, v233, v38
	v_max_f32_e32 v233, v233, v39
	v_max_f32_e32 v233, v233, v40
	v_max_f32_e32 v233, v233, v41
	v_max_f32_e32 v233, v233, v42
	v_max_f32_e32 v233, v233, v43
	v_max_f32_e32 v233, v233, v44
	v_max_f32_e32 v233, v233, v45
	v_max_f32_e32 v233, v233, v46
	v_max_f32_e32 v233, v233, v47
	v_max_f32_e32 v233, v233, v48
	v_max_f32_e32 v233, v233, v49
	v_max_f32_e32 v233, v233, v50
	v_max_f32_e32 v233, v233, v51
	v_max_f32_e32 v233, v233, v52
	v_max_f32_e32 v233, v233, v53
	v_max_f32_e32 v233, v233, v54
	v_max_f32_e32 v233, v233, v55
	v_max_f32_e32 v233, v233, v56
	v_max_f32_e32 v233, v233, v57
	v_max_f32_e32 v233, v233, v58
	v_max_f32_e32 v233, v233, v59
	v_max_f32_e32 v233, v233, v60
	v_max_f32_e32 v233, v233, v61
	v_max_f32_e32 v233, v233, v62
	v_max_f32_e32 v233, v233, v63
	v_max_f32_e32 v233, v233, v64
	v_max_f32_e32 v233, v233, v65
	v_max_f32_e32 v233, v233, v66
	v_max_f32_e32 v233, v233, v67
	v_max_f32_e32 v233, v233, v68
	v_max_f32_e32 v233, v233, v69
	v_max_f32_e32 v233, v233, v70
	v_max_f32_e32 v233, v233, v71
	ds_bpermute_b32 v235, v223, v233
	s_waitcnt lgkmcnt(0)
	v_max_f32_e32 v233, v233, v235
	ds_bpermute_b32 v235, v232, v233
	s_waitcnt lgkmcnt(0)
	v_max_f32_e32 v233, v233, v235
	v_mov_b32_e32 v234, 0
	v_sub_f32_e32 v8, v8, v233
	v_exp_f32_e32 v8, v8
	v_sub_f32_e32 v9, v9, v233
	v_add_f32_e32 v234, v234, v8
	v_exp_f32_e32 v9, v9
	v_sub_f32_e32 v10, v10, v233
	v_add_f32_e32 v234, v234, v9
	v_exp_f32_e32 v10, v10
	v_sub_f32_e32 v11, v11, v233
	v_add_f32_e32 v234, v234, v10
	v_exp_f32_e32 v11, v11
	v_sub_f32_e32 v12, v12, v233
	v_add_f32_e32 v234, v234, v11
	v_exp_f32_e32 v12, v12
	v_sub_f32_e32 v13, v13, v233
	v_add_f32_e32 v234, v234, v12
	v_exp_f32_e32 v13, v13
	v_sub_f32_e32 v14, v14, v233
	v_add_f32_e32 v234, v234, v13
	v_exp_f32_e32 v14, v14
	v_sub_f32_e32 v15, v15, v233
	v_add_f32_e32 v234, v234, v14
	v_exp_f32_e32 v15, v15
	v_sub_f32_e32 v16, v16, v233
	v_add_f32_e32 v234, v234, v15
	v_exp_f32_e32 v16, v16
	v_sub_f32_e32 v17, v17, v233
	v_add_f32_e32 v234, v234, v16
	v_exp_f32_e32 v17, v17
	v_sub_f32_e32 v18, v18, v233
	v_add_f32_e32 v234, v234, v17
	v_exp_f32_e32 v18, v18
	v_sub_f32_e32 v19, v19, v233
	v_add_f32_e32 v234, v234, v18
	v_exp_f32_e32 v19, v19
	v_sub_f32_e32 v20, v20, v233
	v_add_f32_e32 v234, v234, v19
	v_exp_f32_e32 v20, v20
	v_sub_f32_e32 v21, v21, v233
	v_add_f32_e32 v234, v234, v20
	v_exp_f32_e32 v21, v21
	v_sub_f32_e32 v22, v22, v233
	v_add_f32_e32 v234, v234, v21
	v_exp_f32_e32 v22, v22
	v_sub_f32_e32 v23, v23, v233
	v_add_f32_e32 v234, v234, v22
	v_exp_f32_e32 v23, v23
	v_sub_f32_e32 v24, v24, v233
	v_add_f32_e32 v234, v234, v23
	v_exp_f32_e32 v24, v24
	v_sub_f32_e32 v25, v25, v233
	v_add_f32_e32 v234, v234, v24
	v_exp_f32_e32 v25, v25
	v_sub_f32_e32 v26, v26, v233
	v_add_f32_e32 v234, v234, v25
	v_exp_f32_e32 v26, v26
	v_sub_f32_e32 v27, v27, v233
	v_add_f32_e32 v234, v234, v26
	v_exp_f32_e32 v27, v27
	v_sub_f32_e32 v28, v28, v233
	v_add_f32_e32 v234, v234, v27
	v_exp_f32_e32 v28, v28
	v_sub_f32_e32 v29, v29, v233
	v_add_f32_e32 v234, v234, v28
	v_exp_f32_e32 v29, v29
	v_sub_f32_e32 v30, v30, v233
	v_add_f32_e32 v234, v234, v29
	v_exp_f32_e32 v30, v30
	v_sub_f32_e32 v31, v31, v233
	v_add_f32_e32 v234, v234, v30
	v_exp_f32_e32 v31, v31
	v_sub_f32_e32 v32, v32, v233
	v_add_f32_e32 v234, v234, v31
	v_exp_f32_e32 v32, v32
	v_sub_f32_e32 v33, v33, v233
	v_add_f32_e32 v234, v234, v32
	v_exp_f32_e32 v33, v33
	v_sub_f32_e32 v34, v34, v233
	v_add_f32_e32 v234, v234, v33
	v_exp_f32_e32 v34, v34
	v_sub_f32_e32 v35, v35, v233
	v_add_f32_e32 v234, v234, v34
	v_exp_f32_e32 v35, v35
	v_sub_f32_e32 v36, v36, v233
	v_add_f32_e32 v234, v234, v35
	v_exp_f32_e32 v36, v36
	v_sub_f32_e32 v37, v37, v233
	v_add_f32_e32 v234, v234, v36
	v_exp_f32_e32 v37, v37
	v_sub_f32_e32 v38, v38, v233
	v_add_f32_e32 v234, v234, v37
	v_exp_f32_e32 v38, v38
	v_sub_f32_e32 v39, v39, v233
	v_add_f32_e32 v234, v234, v38
	v_exp_f32_e32 v39, v39
	v_sub_f32_e32 v40, v40, v233
	v_add_f32_e32 v234, v234, v39
	v_exp_f32_e32 v40, v40
	v_sub_f32_e32 v41, v41, v233
	v_add_f32_e32 v234, v234, v40
	v_exp_f32_e32 v41, v41
	v_sub_f32_e32 v42, v42, v233
	v_add_f32_e32 v234, v234, v41
	v_exp_f32_e32 v42, v42
	v_sub_f32_e32 v43, v43, v233
	v_add_f32_e32 v234, v234, v42
	v_exp_f32_e32 v43, v43
	v_sub_f32_e32 v44, v44, v233
	v_add_f32_e32 v234, v234, v43
	v_exp_f32_e32 v44, v44
	v_sub_f32_e32 v45, v45, v233
	v_add_f32_e32 v234, v234, v44
	v_exp_f32_e32 v45, v45
	v_sub_f32_e32 v46, v46, v233
	v_add_f32_e32 v234, v234, v45
	v_exp_f32_e32 v46, v46
	v_sub_f32_e32 v47, v47, v233
	v_add_f32_e32 v234, v234, v46
	v_exp_f32_e32 v47, v47
	v_sub_f32_e32 v48, v48, v233
	v_add_f32_e32 v234, v234, v47
	v_exp_f32_e32 v48, v48
	v_sub_f32_e32 v49, v49, v233
	v_add_f32_e32 v234, v234, v48
	v_exp_f32_e32 v49, v49
	v_sub_f32_e32 v50, v50, v233
	v_add_f32_e32 v234, v234, v49
	v_exp_f32_e32 v50, v50
	v_sub_f32_e32 v51, v51, v233
	v_add_f32_e32 v234, v234, v50
	v_exp_f32_e32 v51, v51
	v_sub_f32_e32 v52, v52, v233
	v_add_f32_e32 v234, v234, v51
	v_exp_f32_e32 v52, v52
	v_sub_f32_e32 v53, v53, v233
	v_add_f32_e32 v234, v234, v52
	v_exp_f32_e32 v53, v53
	v_sub_f32_e32 v54, v54, v233
	v_add_f32_e32 v234, v234, v53
	v_exp_f32_e32 v54, v54
	v_sub_f32_e32 v55, v55, v233
	v_add_f32_e32 v234, v234, v54
	v_exp_f32_e32 v55, v55
	v_sub_f32_e32 v56, v56, v233
	v_add_f32_e32 v234, v234, v55
	v_exp_f32_e32 v56, v56
	v_sub_f32_e32 v57, v57, v233
	v_add_f32_e32 v234, v234, v56
	v_exp_f32_e32 v57, v57
	v_sub_f32_e32 v58, v58, v233
	v_add_f32_e32 v234, v234, v57
	v_exp_f32_e32 v58, v58
	v_sub_f32_e32 v59, v59, v233
	v_add_f32_e32 v234, v234, v58
	v_exp_f32_e32 v59, v59
	v_sub_f32_e32 v60, v60, v233
	v_add_f32_e32 v234, v234, v59
	v_exp_f32_e32 v60, v60
	v_sub_f32_e32 v61, v61, v233
	v_add_f32_e32 v234, v234, v60
	v_exp_f32_e32 v61, v61
	v_sub_f32_e32 v62, v62, v233
	v_add_f32_e32 v234, v234, v61
	v_exp_f32_e32 v62, v62
	v_sub_f32_e32 v63, v63, v233
	v_add_f32_e32 v234, v234, v62
	v_exp_f32_e32 v63, v63
	v_sub_f32_e32 v64, v64, v233
	v_add_f32_e32 v234, v234, v63
	v_exp_f32_e32 v64, v64
	v_sub_f32_e32 v65, v65, v233
	v_add_f32_e32 v234, v234, v64
	v_exp_f32_e32 v65, v65
	v_sub_f32_e32 v66, v66, v233
	v_add_f32_e32 v234, v234, v65
	v_exp_f32_e32 v66, v66
	v_sub_f32_e32 v67, v67, v233
	v_add_f32_e32 v234, v234, v66
	v_exp_f32_e32 v67, v67
	v_sub_f32_e32 v68, v68, v233
	v_add_f32_e32 v234, v234, v67
	v_exp_f32_e32 v68, v68
	v_sub_f32_e32 v69, v69, v233
	v_add_f32_e32 v234, v234, v68
	v_exp_f32_e32 v69, v69
	v_sub_f32_e32 v70, v70, v233
	v_add_f32_e32 v234, v234, v69
	v_exp_f32_e32 v70, v70
	v_sub_f32_e32 v71, v71, v233
	v_add_f32_e32 v234, v234, v70
	v_exp_f32_e32 v71, v71
	s_nop 0
	v_add_f32_e32 v234, v234, v71
	ds_bpermute_b32 v235, v223, v234
	v_cvt_pk_bf16_f32 v8, v8, v9
	v_cvt_pk_bf16_f32 v9, v10, v11
	v_cvt_pk_bf16_f32 v10, v12, v13
	v_cvt_pk_bf16_f32 v11, v14, v15
	v_cvt_pk_bf16_f32 v16, v16, v17
	v_cvt_pk_bf16_f32 v17, v18, v19
	v_cvt_pk_bf16_f32 v18, v20, v21
	v_cvt_pk_bf16_f32 v19, v22, v23
	v_cvt_pk_bf16_f32 v24, v24, v25
	v_cvt_pk_bf16_f32 v25, v26, v27
	v_cvt_pk_bf16_f32 v26, v28, v29
	v_cvt_pk_bf16_f32 v27, v30, v31
	v_cvt_pk_bf16_f32 v32, v32, v33
	v_cvt_pk_bf16_f32 v33, v34, v35
	v_cvt_pk_bf16_f32 v34, v36, v37
	v_cvt_pk_bf16_f32 v35, v38, v39
	v_cvt_pk_bf16_f32 v40, v40, v41
	v_cvt_pk_bf16_f32 v41, v42, v43
	v_cvt_pk_bf16_f32 v42, v44, v45
	v_cvt_pk_bf16_f32 v43, v46, v47
	v_cvt_pk_bf16_f32 v48, v48, v49
	v_cvt_pk_bf16_f32 v49, v50, v51
	v_cvt_pk_bf16_f32 v50, v52, v53
	v_cvt_pk_bf16_f32 v51, v54, v55
	v_cvt_pk_bf16_f32 v56, v56, v57
	v_cvt_pk_bf16_f32 v57, v58, v59
	v_cvt_pk_bf16_f32 v58, v60, v61
	v_cvt_pk_bf16_f32 v59, v62, v63
	v_cvt_pk_bf16_f32 v64, v64, v65
	v_cvt_pk_bf16_f32 v65, v66, v67
	v_cvt_pk_bf16_f32 v66, v68, v69
	v_cvt_pk_bf16_f32 v67, v70, v71
	s_waitcnt lgkmcnt(0)
	v_add_f32_e32 v234, v234, v235
	ds_bpermute_b32 v235, v232, v234
	s_waitcnt lgkmcnt(0)
	v_add_f32_e32 v234, v234, v235
	s_barrier
	v_mov_b32_e32 v138, v136
	ds_read_b128 v[12:15], v138 offset:16
	ds_read_b128 v[20:23], v138 offset:16400
	ds_read_b128 v[28:31], v138 offset:32784
	ds_read_b128 v[36:39], v138 offset:49168
	v_xor_b32_e32 v138, 128, v136
	ds_read_b128 v[44:47], v138 offset:16
	ds_read_b128 v[52:55], v138 offset:16400
	ds_read_b128 v[60:63], v138 offset:32784
	ds_read_b128 v[68:71], v138 offset:49168
	v_xor_b32_e32 v138, 256, v136
	ds_read_b128 v[194:197], v138 offset:16
	ds_read_b128 v[198:201], v138 offset:16400
	ds_read_b128 v[202:205], v138 offset:32784
	ds_read_b128 v[206:209], v138 offset:49168
	s_waitcnt lgkmcnt(8)
	v_mfma_f32_16x16x32_bf16 v[178:181], v[12:15], v[8:11], v[178:181]
	v_mfma_f32_16x16x32_bf16 v[182:185], v[20:23], v[8:11], v[182:185]
	v_mfma_f32_16x16x32_bf16 v[186:189], v[28:31], v[8:11], v[186:189]
	v_mfma_f32_16x16x32_bf16 v[190:193], v[36:39], v[8:11], v[190:193]
	v_xor_b32_e32 v138, 384, v136
	ds_read_b128 v[12:15], v138 offset:16
	ds_read_b128 v[20:23], v138 offset:16400
	ds_read_b128 v[28:31], v138 offset:32784
	ds_read_b128 v[36:39], v138 offset:49168
	s_waitcnt lgkmcnt(8)
	v_mfma_f32_16x16x32_bf16 v[178:181], v[44:47], v[16:19], v[178:181]
	v_mfma_f32_16x16x32_bf16 v[182:185], v[52:55], v[16:19], v[182:185]
	v_mfma_f32_16x16x32_bf16 v[186:189], v[60:63], v[16:19], v[186:189]
	v_mfma_f32_16x16x32_bf16 v[190:193], v[68:71], v[16:19], v[190:193]
	v_xor_b32_e32 v138, 512, v136
	ds_read_b128 v[44:47], v138 offset:16
	ds_read_b128 v[52:55], v138 offset:16400
	ds_read_b128 v[60:63], v138 offset:32784
	ds_read_b128 v[68:71], v138 offset:49168
	s_waitcnt lgkmcnt(8)
	v_mfma_f32_16x16x32_bf16 v[178:181], v[194:197], v[24:27], v[178:181]
	v_mfma_f32_16x16x32_bf16 v[182:185], v[198:201], v[24:27], v[182:185]
	v_mfma_f32_16x16x32_bf16 v[186:189], v[202:205], v[24:27], v[186:189]
	v_mfma_f32_16x16x32_bf16 v[190:193], v[206:209], v[24:27], v[190:193]
	v_xor_b32_e32 v138, 640, v136
	ds_read_b128 v[194:197], v138 offset:16
	ds_read_b128 v[198:201], v138 offset:16400
	ds_read_b128 v[202:205], v138 offset:32784
	ds_read_b128 v[206:209], v138 offset:49168
	s_waitcnt lgkmcnt(8)
	v_mfma_f32_16x16x32_bf16 v[178:181], v[12:15], v[32:35], v[178:181]
	v_mfma_f32_16x16x32_bf16 v[182:185], v[20:23], v[32:35], v[182:185]
	v_mfma_f32_16x16x32_bf16 v[186:189], v[28:31], v[32:35], v[186:189]
	v_mfma_f32_16x16x32_bf16 v[190:193], v[36:39], v[32:35], v[190:193]
	v_xor_b32_e32 v138, 768, v136
	ds_read_b128 v[12:15], v138 offset:16
	ds_read_b128 v[20:23], v138 offset:16400
	ds_read_b128 v[28:31], v138 offset:32784
	ds_read_b128 v[36:39], v138 offset:49168
	s_waitcnt lgkmcnt(8)
	v_mfma_f32_16x16x32_bf16 v[178:181], v[44:47], v[40:43], v[178:181]
	v_mfma_f32_16x16x32_bf16 v[182:185], v[52:55], v[40:43], v[182:185]
	v_mfma_f32_16x16x32_bf16 v[186:189], v[60:63], v[40:43], v[186:189]
	v_mfma_f32_16x16x32_bf16 v[190:193], v[68:71], v[40:43], v[190:193]
	v_xor_b32_e32 v138, 896, v136
	ds_read_b128 v[44:47], v138 offset:16
	ds_read_b128 v[52:55], v138 offset:16400
	ds_read_b128 v[60:63], v138 offset:32784
	ds_read_b128 v[68:71], v138 offset:49168
	s_waitcnt lgkmcnt(8)
	v_mfma_f32_16x16x32_bf16 v[178:181], v[194:197], v[48:51], v[178:181]
	v_mfma_f32_16x16x32_bf16 v[182:185], v[198:201], v[48:51], v[182:185]
	v_mfma_f32_16x16x32_bf16 v[186:189], v[202:205], v[48:51], v[186:189]
	v_mfma_f32_16x16x32_bf16 v[190:193], v[206:209], v[48:51], v[190:193]
	s_waitcnt lgkmcnt(4)
	v_mfma_f32_16x16x32_bf16 v[178:181], v[12:15], v[56:59], v[178:181]
	v_mfma_f32_16x16x32_bf16 v[182:185], v[20:23], v[56:59], v[182:185]
	v_mfma_f32_16x16x32_bf16 v[186:189], v[28:31], v[56:59], v[186:189]
	v_mfma_f32_16x16x32_bf16 v[190:193], v[36:39], v[56:59], v[190:193]
	s_waitcnt lgkmcnt(0)
	v_mfma_f32_16x16x32_bf16 v[178:181], v[44:47], v[64:67], v[178:181]
	v_mfma_f32_16x16x32_bf16 v[182:185], v[52:55], v[64:67], v[182:185]
	v_mfma_f32_16x16x32_bf16 v[186:189], v[60:63], v[64:67], v[186:189]
	v_mfma_f32_16x16x32_bf16 v[190:193], v[68:71], v[64:67], v[190:193]
	v_div_scale_f32 v235, s[36:37], v234, v234, 1.0
	v_rcp_f32_e32 v236, v235
	s_nop 0
	v_fma_f32 v237, -v235, v236, 1.0
	v_fmac_f32_e32 v236, v237, v236
	v_div_scale_f32 v237, vcc, 1.0, v234, 1.0
	v_mul_f32_e32 v240, v237, v236
	v_fma_f32 v241, -v235, v240, v237
	v_fmac_f32_e32 v240, v241, v236
	v_fma_f32 v235, -v235, v240, v237
	v_div_fmas_f32 v235, v235, v236, v240
	v_div_fixup_f32 v233, v235, v234, 1.0
	s_nop 3
	v_mul_f32_e32 v178, v178, v233
	v_mul_f32_e32 v179, v179, v233
	v_mul_f32_e32 v180, v180, v233
	v_mul_f32_e32 v181, v181, v233
	v_cvt_pk_bf16_f32 v178, v178, v179
	v_cvt_pk_bf16_f32 v179, v180, v181
	global_store_dwordx2 v222, v[178:179], s[32:33]
	v_mul_f32_e32 v182, v182, v233
	v_mul_f32_e32 v183, v183, v233
	v_mul_f32_e32 v184, v184, v233
	v_mul_f32_e32 v185, v185, v233
	v_cvt_pk_bf16_f32 v182, v182, v183
	v_cvt_pk_bf16_f32 v183, v184, v185
	global_store_dwordx2 v222, v[182:183], s[32:33] offset:32
	v_mul_f32_e32 v186, v186, v233
	v_mul_f32_e32 v187, v187, v233
	v_mul_f32_e32 v188, v188, v233
	v_mul_f32_e32 v189, v189, v233
	v_cvt_pk_bf16_f32 v186, v186, v187
	v_cvt_pk_bf16_f32 v187, v188, v189
	global_store_dwordx2 v222, v[186:187], s[32:33] offset:64
	v_mul_f32_e32 v190, v190, v233
	v_mul_f32_e32 v191, v191, v233
	v_mul_f32_e32 v192, v192, v233
	v_mul_f32_e32 v193, v193, v233
	v_cvt_pk_bf16_f32 v190, v190, v191
	v_cvt_pk_bf16_f32 v191, v192, v193
	global_store_dwordx2 v222, v[190:191], s[32:33] offset:96
	s_add_u32 s14, s14, 1
	s_bfe_u32 s36, s98, 0x80008
	s_cmp_lt_u32 s14, s36
	s_cbranch_scc1 .Lna_tile
	v_readlane_b32 s0, v245, 0
	v_readlane_b32 s1, v245, 1
	v_readlane_b32 s2, v245, 2
	v_readlane_b32 s3, v245, 3
	v_readlane_b32 s4, v245, 4
	v_readlane_b32 s5, v245, 5
	v_readlane_b32 s6, v245, 6
	v_readlane_b32 s7, v245, 7
	v_readlane_b32 s8, v245, 8
	v_readlane_b32 s9, v245, 9
	v_readlane_b32 s10, v245, 10
	v_readlane_b32 s11, v245, 11
	v_readlane_b32 s12, v245, 12
	v_readlane_b32 s13, v245, 13
	v_readlane_b32 s14, v245, 14
	v_readlane_b32 s15, v245, 15
	v_readlane_b32 s16, v245, 16
	v_readlane_b32 s17, v245, 17
	v_readlane_b32 s18, v245, 18
	v_readlane_b32 s19, v245, 19
	v_readlane_b32 s20, v245, 20
	v_readlane_b32 s21, v245, 21
	v_readlane_b32 s22, v245, 22
	v_readlane_b32 s23, v245, 23
	v_readlane_b32 s24, v245, 24
	v_readlane_b32 s25, v245, 25
	v_readlane_b32 s26, v245, 26
	v_readlane_b32 s27, v245, 27
	v_readlane_b32 s28, v245, 28
	v_readlane_b32 s29, v245, 29
	v_readlane_b32 s30, v245, 30
	v_readlane_b32 s31, v245, 31
	v_readlane_b32 s32, v245, 32
	v_readlane_b32 s33, v245, 33
	v_readlane_b32 s34, v245, 34
	v_readlane_b32 s35, v245, 35
	v_readlane_b32 s36, v245, 36
	v_readlane_b32 s37, v245, 37
	v_readlane_b32 s38, v245, 38
	v_readlane_b32 s39, v245, 39
	v_readlane_b32 s40, v245, 40
	v_readlane_b32 s41, v245, 41
	v_readlane_b32 s42, v245, 42
	v_readlane_b32 s43, v245, 43
	v_readlane_b32 s44, v245, 44
	v_readlane_b32 s45, v245, 45
	v_readlane_b32 s46, v245, 46
	v_readlane_b32 s47, v245, 47
	v_readlane_b32 s48, v245, 48
	v_readlane_b32 s49, v245, 49
	v_readlane_b32 s50, v245, 50
	v_readlane_b32 s51, v245, 51
	v_readlane_b32 s52, v245, 52
	v_readlane_b32 s53, v245, 53
	v_readlane_b32 s54, v245, 54
	v_readlane_b32 s55, v245, 55
	v_readlane_b32 s56, v245, 56
	v_readlane_b32 s57, v245, 57
	v_readlane_b32 s58, v245, 58
	v_readlane_b32 s59, v245, 59
	v_readlane_b32 s60, v245, 60
	v_readlane_b32 s61, v245, 61
	v_readlane_b32 s62, v245, 62
	v_readlane_b32 s63, v245, 63
	v_readlane_b32 s64, v244, 0
	v_readlane_b32 s65, v244, 1
	v_readlane_b32 s66, v244, 2
	v_readlane_b32 s67, v244, 3
	v_readlane_b32 s68, v244, 4
	v_readlane_b32 s69, v244, 5
	v_readlane_b32 s70, v244, 6
	v_readlane_b32 s71, v244, 7
	v_readlane_b32 s72, v244, 8
	v_readlane_b32 s73, v244, 9
	v_readlane_b32 s74, v244, 10
	v_readlane_b32 s75, v244, 11
	v_readlane_b32 s76, v244, 12
	v_readlane_b32 s77, v244, 13
	v_readlane_b32 s78, v244, 14
	v_readlane_b32 s79, v244, 15
	s_add_u32 s98, s98, 0x1000000
	s_branch .Lp2_disp
.LBB0_1074:
	s_mov_b64 exec, -1
	v_writelane_b32 v115, s0, 0
	v_writelane_b32 v115, s1, 1
	v_writelane_b32 v115, s2, 2
	v_writelane_b32 v115, s3, 3
	v_writelane_b32 v115, s4, 4
	v_writelane_b32 v115, s5, 5
	v_writelane_b32 v115, s6, 6
	v_writelane_b32 v115, s7, 7
	v_writelane_b32 v115, s8, 8
	v_writelane_b32 v115, s9, 9
	v_writelane_b32 v115, s10, 10
	v_writelane_b32 v115, s11, 11
	v_writelane_b32 v115, s12, 12
	v_writelane_b32 v115, s13, 13
	v_writelane_b32 v115, s14, 14
	v_writelane_b32 v115, s15, 15
	v_writelane_b32 v115, s16, 16
	v_writelane_b32 v115, s17, 17
	v_writelane_b32 v115, s18, 18
	v_writelane_b32 v115, s19, 19
	v_writelane_b32 v115, s20, 20
	v_writelane_b32 v115, s21, 21
	v_writelane_b32 v115, s22, 22
	v_writelane_b32 v115, s23, 23
	v_writelane_b32 v115, s24, 24
	v_writelane_b32 v115, s25, 25
	v_writelane_b32 v115, s26, 26
	v_writelane_b32 v115, s27, 27
	v_writelane_b32 v115, s28, 28
	v_writelane_b32 v115, s29, 29
	v_writelane_b32 v115, s30, 30
	v_writelane_b32 v115, s31, 31
	v_writelane_b32 v115, s32, 32
	v_writelane_b32 v115, s33, 33
	v_writelane_b32 v115, s34, 34
	v_writelane_b32 v115, s35, 35
	v_writelane_b32 v115, s36, 36
	v_writelane_b32 v115, s37, 37
	v_writelane_b32 v115, s38, 38
	v_writelane_b32 v115, s39, 39
	v_writelane_b32 v115, s40, 40
	v_writelane_b32 v115, s41, 41
	v_writelane_b32 v115, s42, 42
	v_writelane_b32 v115, s43, 43
	v_writelane_b32 v115, s44, 44
	v_writelane_b32 v115, s45, 45
	v_writelane_b32 v115, s46, 46
	v_writelane_b32 v115, s47, 47
	v_lshrrev_b32_e32 v114, 6, v225
	s_load_dwordx2 s[10:11], s[100:101], 0xb0
	s_load_dwordx2 s[12:13], s[100:101], 0x30
	s_load_dwordx2 s[14:15], s[100:101], 0x38
	s_load_dwordx2 s[16:17], s[100:101], 0xa8
	v_readfirstlane_b32 s4, v114
	v_and_b32_e32 v109, 0xff, v225
	v_lshlrev_b32_e32 v109, 1, v109
	v_lshlrev_b32_e32 v112, 1, v109
	v_add_u32_e32 v113, 0x1000, v112
	s_nop 1
	s_lshr_b32 s5, s4, 2
	s_lshl_b32 s6, s99, 1
	s_add_u32 s6, s6, s5
	s_and_b32 s46, s98, 0xff
	s_lshl_b32 s46, s46, 9
	s_add_u32 s6, s6, s46
	s_bfe_u32 s47, s98, 0x80008
	s_lshl_b32 s47, s47, 9
	s_waitcnt lgkmcnt(0)

.Lcv_nn7:
	s_add_u32 s6, s6, 0x200
	s_cmp_lt_u32 s6, s47
	s_cbranch_scc1 .Lcv_tile
	v_readlane_b32 s0, v115, 0
	v_readlane_b32 s1, v115, 1
	v_readlane_b32 s2, v115, 2
	v_readlane_b32 s3, v115, 3
	v_readlane_b32 s4, v115, 4
	v_readlane_b32 s5, v115, 5
	v_readlane_b32 s6, v115, 6
	v_readlane_b32 s7, v115, 7
	v_readlane_b32 s8, v115, 8
	v_readlane_b32 s9, v115, 9
	v_readlane_b32 s10, v115, 10
	v_readlane_b32 s11, v115, 11
	v_readlane_b32 s12, v115, 12
	v_readlane_b32 s13, v115, 13
	v_readlane_b32 s14, v115, 14
	v_readlane_b32 s15, v115, 15
	v_readlane_b32 s16, v115, 16
	v_readlane_b32 s17, v115, 17
	v_readlane_b32 s18, v115, 18
	v_readlane_b32 s19, v115, 19
	v_readlane_b32 s20, v115, 20
	v_readlane_b32 s21, v115, 21
	v_readlane_b32 s22, v115, 22
	v_readlane_b32 s23, v115, 23
	v_readlane_b32 s24, v115, 24
	v_readlane_b32 s25, v115, 25
	v_readlane_b32 s26, v115, 26
	v_readlane_b32 s27, v115, 27
	v_readlane_b32 s28, v115, 28
	v_readlane_b32 s29, v115, 29
	v_readlane_b32 s30, v115, 30
	v_readlane_b32 s31, v115, 31
	v_readlane_b32 s32, v115, 32
	v_readlane_b32 s33, v115, 33
	v_readlane_b32 s34, v115, 34
	v_readlane_b32 s35, v115, 35
	v_readlane_b32 s36, v115, 36
	v_readlane_b32 s37, v115, 37
	v_readlane_b32 s38, v115, 38
	v_readlane_b32 s39, v115, 39
	v_readlane_b32 s40, v115, 40
	v_readlane_b32 s41, v115, 41
	v_readlane_b32 s42, v115, 42
	v_readlane_b32 s43, v115, 43
	v_readlane_b32 s44, v115, 44
	v_readlane_b32 s45, v115, 45
	v_readlane_b32 s46, v115, 46
	v_readlane_b32 s47, v115, 47
	s_add_u32 s98, s98, 0x1000000
	s_branch .Lp2_disp
